# PV ring: one lgkmcnt wait per MFMA pair (16 instead of 32 waits per tile)
# baseline (speedup 1.0000x reference)
.LBB0_517:
	v_cndmask_b32_e64 v231, v234, v231, s[4:5]
	v_mul_f32_e32 v192, 0xbe0293ee, v231
	v_fmamk_f32 v144, v144, 0x3e0293ee, v192
	v_fmamk_f32 v145, v145, 0x3e0293ee, v192
	v_fmamk_f32 v146, v146, 0x3e0293ee, v192
	v_fmamk_f32 v147, v147, 0x3e0293ee, v192
	v_fmamk_f32 v148, v148, 0x3e0293ee, v192
	v_fmamk_f32 v149, v149, 0x3e0293ee, v192
	v_fmamk_f32 v150, v150, 0x3e0293ee, v192
	v_fmamk_f32 v151, v151, 0x3e0293ee, v192
	v_fmamk_f32 v152, v152, 0x3e0293ee, v192
	v_fmamk_f32 v153, v153, 0x3e0293ee, v192
	v_fmamk_f32 v154, v154, 0x3e0293ee, v192
	v_fmamk_f32 v155, v155, 0x3e0293ee, v192
	v_fmamk_f32 v156, v156, 0x3e0293ee, v192
	v_fmamk_f32 v157, v157, 0x3e0293ee, v192
	v_fmamk_f32 v158, v158, 0x3e0293ee, v192
	v_fmamk_f32 v159, v159, 0x3e0293ee, v192
	v_fmamk_f32 v128, v128, 0x3e0293ee, v192
	v_fmamk_f32 v129, v129, 0x3e0293ee, v192
	v_fmamk_f32 v130, v130, 0x3e0293ee, v192
	v_fmamk_f32 v131, v131, 0x3e0293ee, v192
	v_fmamk_f32 v132, v132, 0x3e0293ee, v192
	v_fmamk_f32 v133, v133, 0x3e0293ee, v192
	v_fmamk_f32 v134, v134, 0x3e0293ee, v192
	v_fmamk_f32 v135, v135, 0x3e0293ee, v192
	v_fmamk_f32 v136, v136, 0x3e0293ee, v192
	v_fmamk_f32 v137, v137, 0x3e0293ee, v192
	v_fmamk_f32 v138, v138, 0x3e0293ee, v192
	v_fmamk_f32 v139, v139, 0x3e0293ee, v192
	v_fmamk_f32 v140, v140, 0x3e0293ee, v192
	v_fmamk_f32 v141, v141, 0x3e0293ee, v192
	v_fmamk_f32 v142, v142, 0x3e0293ee, v192
	v_fmac_f32_e32 v192, 0x3e0293ee, v143
	v_exp_f32_e32 v143, v144
	v_exp_f32_e32 v145, v145
	v_exp_f32_e32 v146, v146
	v_exp_f32_e32 v147, v147
	v_exp_f32_e32 v148, v148
	v_exp_f32_e32 v193, v128
	v_exp_f32_e32 v149, v149
	v_add_f32_e32 v128, v145, v143
	v_exp_f32_e32 v150, v150
	v_add_f32_e32 v128, v146, v128
	v_exp_f32_e32 v151, v151
	v_add_f32_e32 v128, v147, v128
	v_exp_f32_e32 v152, v152
	v_add_f32_e32 v128, v148, v128
	v_exp_f32_e32 v153, v153
	v_add_f32_e32 v128, v149, v128
	v_exp_f32_e32 v154, v154
	v_add_f32_e32 v128, v150, v128
	v_exp_f32_e32 v155, v155
	v_add_f32_e32 v128, v151, v128
	v_exp_f32_e32 v156, v156
	v_add_f32_e32 v128, v152, v128
	v_exp_f32_e32 v157, v157
	v_add_f32_e32 v128, v153, v128
	v_exp_f32_e32 v158, v158
	v_add_f32_e32 v128, v154, v128
	v_exp_f32_e32 v159, v159
	v_add_f32_e32 v128, v155, v128
	v_add_f32_e32 v128, v156, v128
	v_exp_f32_e32 v194, v129
	v_add_f32_e32 v128, v157, v128
	v_exp_f32_e32 v195, v130
	v_add_f32_e32 v128, v158, v128
	v_exp_f32_e32 v196, v131
	v_add_f32_e32 v128, v159, v128
	v_exp_f32_e32 v197, v132
	v_add_f32_e32 v128, v193, v128
	v_exp_f32_e32 v198, v133
	v_add_f32_e32 v128, v194, v128
	v_exp_f32_e32 v199, v134
	v_add_f32_e32 v128, v195, v128
	v_exp_f32_e32 v135, v135
	v_add_f32_e32 v128, v196, v128
	v_exp_f32_e32 v200, v136
	v_add_f32_e32 v128, v197, v128
	v_exp_f32_e32 v201, v137
	v_add_f32_e32 v128, v198, v128
	v_exp_f32_e32 v202, v138
	v_add_f32_e32 v128, v199, v128
	v_exp_f32_e32 v203, v139
	v_add_f32_e32 v128, v135, v128
	v_exp_f32_e32 v204, v140
	v_add_f32_e32 v128, v200, v128
	v_exp_f32_e32 v205, v141
	v_add_f32_e32 v128, v201, v128
	v_exp_f32_e32 v206, v142
	v_add_f32_e32 v128, v202, v128
	v_exp_f32_e32 v192, v192
	v_add_f32_e32 v128, v203, v128
	v_add_f32_e32 v128, v204, v128
	v_add_f32_e32 v128, v205, v128
	v_add_f32_e32 v128, v206, v128
	v_add_f32_e32 v128, v192, v128
	v_mov_b32_e32 v129, v128
	s_nop 1
	v_permlane32_swap_b32_e32 v128, v129
	v_add_f32_e32 v144, v128, v129
	v_fmac_f32_e32 v144, v232, v233
	v_cvt_pk_bf16_f32 v128, v143, v145
	v_cvt_pk_bf16_f32 v129, v146, v147
	v_cvt_pk_bf16_f32 v130, v148, v149
	v_cvt_pk_bf16_f32 v131, v150, v151
	v_cvt_pk_bf16_f32 v136, v152, v153
	v_cvt_pk_bf16_f32 v137, v154, v155
	v_cvt_pk_bf16_f32 v138, v156, v157
	v_cvt_pk_bf16_f32 v139, v158, v159
	v_cvt_pk_bf16_f32 v132, v193, v194
	v_cvt_pk_bf16_f32 v133, v195, v196
	v_cvt_pk_bf16_f32 v134, v197, v198
	v_cvt_pk_bf16_f32 v135, v199, v135
	v_cvt_pk_bf16_f32 v140, v200, v201
	v_cvt_pk_bf16_f32 v141, v202, v203
	v_cvt_pk_bf16_f32 v142, v204, v205
	v_cvt_pk_bf16_f32 v143, v206, v192
	v_lshl_add_u32 v145, s76, 15, v230
	ds_read_b64_tr_b16 v[146:147], v145 offset:0
	ds_read_b64_tr_b16 v[148:149], v145 offset:4096
	ds_read_b64_tr_b16 v[150:151], v145 offset:8192
	ds_read_b64_tr_b16 v[152:153], v145 offset:12288
	ds_read_b64_tr_b16 v[154:155], v145 offset:16384
	ds_read_b64_tr_b16 v[156:157], v145 offset:20480
	ds_read_b64_tr_b16 v[192:193], v145 offset:24576
	ds_read_b64_tr_b16 v[194:195], v145 offset:28672
	ds_read_b64_tr_b16 v[196:197], v145 offset:512
	ds_read_b64_tr_b16 v[198:199], v145 offset:4608
	ds_read_b64_tr_b16 v[200:201], v145 offset:8704
	ds_read_b64_tr_b16 v[202:203], v145 offset:12800
	ds_read_b64_tr_b16 v[204:205], v145 offset:16896
	ds_read_b64_tr_b16 v[206:207], v145 offset:20992
	s_waitcnt lgkmcnt(10)
	s_nop 0
	v_mfma_f32_32x32x16_bf16 v[0:15], v[128:131], v[146:149], v[0:15]
	v_mfma_f32_32x32x16_bf16 v[0:15], v[136:139], v[150:153], v[0:15]
	ds_read_b64_tr_b16 v[232:233], v145 offset:25088
	ds_read_b64_tr_b16 v[234:235], v145 offset:29184
	ds_read_b64_tr_b16 v[146:147], v145 offset:1024
	ds_read_b64_tr_b16 v[148:149], v145 offset:5120
	s_waitcnt lgkmcnt(10)
	v_mfma_f32_32x32x16_bf16 v[0:15], v[132:135], v[154:157], v[0:15]
	v_mfma_f32_32x32x16_bf16 v[0:15], v[140:143], v[192:195], v[0:15]
	ds_read_b64_tr_b16 v[150:151], v145 offset:9216
	ds_read_b64_tr_b16 v[152:153], v145 offset:13312
	ds_read_b64_tr_b16 v[154:155], v145 offset:17408
	ds_read_b64_tr_b16 v[156:157], v145 offset:21504
	s_waitcnt lgkmcnt(10)
	v_mfma_f32_32x32x16_bf16 v[112:127], v[128:131], v[196:199], v[112:127]
	v_mfma_f32_32x32x16_bf16 v[112:127], v[136:139], v[200:203], v[112:127]
	ds_read_b64_tr_b16 v[192:193], v145 offset:25600
	ds_read_b64_tr_b16 v[194:195], v145 offset:29696
	ds_read_b64_tr_b16 v[196:197], v145 offset:1536
	ds_read_b64_tr_b16 v[198:199], v145 offset:5632
	s_waitcnt lgkmcnt(10)
	v_mfma_f32_32x32x16_bf16 v[112:127], v[132:135], v[204:207], v[112:127]
	v_mfma_f32_32x32x16_bf16 v[112:127], v[140:143], v[232:235], v[112:127]
	ds_read_b64_tr_b16 v[200:201], v145 offset:9728
	ds_read_b64_tr_b16 v[202:203], v145 offset:13824
	ds_read_b64_tr_b16 v[204:205], v145 offset:17920
	ds_read_b64_tr_b16 v[206:207], v145 offset:22016
	s_waitcnt lgkmcnt(10)
	v_mfma_f32_32x32x16_bf16 v[96:111], v[128:131], v[146:149], v[96:111]
	v_mfma_f32_32x32x16_bf16 v[96:111], v[136:139], v[150:153], v[96:111]
	ds_read_b64_tr_b16 v[232:233], v145 offset:26112
	ds_read_b64_tr_b16 v[234:235], v145 offset:30208
	ds_read_b64_tr_b16 v[146:147], v145 offset:2048
	ds_read_b64_tr_b16 v[148:149], v145 offset:6144
	s_waitcnt lgkmcnt(10)
	v_mfma_f32_32x32x16_bf16 v[96:111], v[132:135], v[154:157], v[96:111]
	v_mfma_f32_32x32x16_bf16 v[96:111], v[140:143], v[192:195], v[96:111]
	ds_read_b64_tr_b16 v[150:151], v145 offset:10240
	ds_read_b64_tr_b16 v[152:153], v145 offset:14336
	ds_read_b64_tr_b16 v[154:155], v145 offset:18432
	ds_read_b64_tr_b16 v[156:157], v145 offset:22528
	s_waitcnt lgkmcnt(10)
	v_mfma_f32_32x32x16_bf16 v[80:95], v[128:131], v[196:199], v[80:95]
	v_mfma_f32_32x32x16_bf16 v[80:95], v[136:139], v[200:203], v[80:95]
	ds_read_b64_tr_b16 v[192:193], v145 offset:26624
	ds_read_b64_tr_b16 v[194:195], v145 offset:30720
	ds_read_b64_tr_b16 v[196:197], v145 offset:2560
	ds_read_b64_tr_b16 v[198:199], v145 offset:6656
	s_waitcnt lgkmcnt(10)
	v_mfma_f32_32x32x16_bf16 v[80:95], v[132:135], v[204:207], v[80:95]
	v_mfma_f32_32x32x16_bf16 v[80:95], v[140:143], v[232:235], v[80:95]
	ds_read_b64_tr_b16 v[200:201], v145 offset:10752
	ds_read_b64_tr_b16 v[202:203], v145 offset:14848
	ds_read_b64_tr_b16 v[204:205], v145 offset:18944
	ds_read_b64_tr_b16 v[206:207], v145 offset:23040
	s_waitcnt lgkmcnt(10)
	v_mfma_f32_32x32x16_bf16 v[64:79], v[128:131], v[146:149], v[64:79]
	v_mfma_f32_32x32x16_bf16 v[64:79], v[136:139], v[150:153], v[64:79]
	ds_read_b64_tr_b16 v[232:233], v145 offset:27136
	ds_read_b64_tr_b16 v[234:235], v145 offset:31232
	ds_read_b64_tr_b16 v[146:147], v145 offset:3072
	ds_read_b64_tr_b16 v[148:149], v145 offset:7168
	s_waitcnt lgkmcnt(10)
	v_mfma_f32_32x32x16_bf16 v[64:79], v[132:135], v[154:157], v[64:79]
	v_mfma_f32_32x32x16_bf16 v[64:79], v[140:143], v[192:195], v[64:79]
	ds_read_b64_tr_b16 v[150:151], v145 offset:11264
	ds_read_b64_tr_b16 v[152:153], v145 offset:15360
	ds_read_b64_tr_b16 v[154:155], v145 offset:19456
	ds_read_b64_tr_b16 v[156:157], v145 offset:23552
	s_waitcnt lgkmcnt(10)
	v_mfma_f32_32x32x16_bf16 v[48:63], v[128:131], v[196:199], v[48:63]
	v_mfma_f32_32x32x16_bf16 v[48:63], v[136:139], v[200:203], v[48:63]
	ds_read_b64_tr_b16 v[192:193], v145 offset:27648
	ds_read_b64_tr_b16 v[194:195], v145 offset:31744
	ds_read_b64_tr_b16 v[196:197], v145 offset:3584
	ds_read_b64_tr_b16 v[198:199], v145 offset:7680
	s_waitcnt lgkmcnt(10)
	v_mfma_f32_32x32x16_bf16 v[48:63], v[132:135], v[204:207], v[48:63]
	v_mfma_f32_32x32x16_bf16 v[48:63], v[140:143], v[232:235], v[48:63]
	ds_read_b64_tr_b16 v[200:201], v145 offset:11776
	ds_read_b64_tr_b16 v[202:203], v145 offset:15872
	ds_read_b64_tr_b16 v[204:205], v145 offset:19968
	ds_read_b64_tr_b16 v[206:207], v145 offset:24064
	s_waitcnt lgkmcnt(10)
	v_mfma_f32_32x32x16_bf16 v[32:47], v[128:131], v[146:149], v[32:47]
	v_mfma_f32_32x32x16_bf16 v[32:47], v[136:139], v[150:153], v[32:47]
	ds_read_b64_tr_b16 v[232:233], v145 offset:28160
	ds_read_b64_tr_b16 v[234:235], v145 offset:32256
	s_waitcnt lgkmcnt(8)
	v_mfma_f32_32x32x16_bf16 v[32:47], v[132:135], v[154:157], v[32:47]
	v_mfma_f32_32x32x16_bf16 v[32:47], v[140:143], v[192:195], v[32:47]
	s_waitcnt lgkmcnt(4)
	v_mfma_f32_32x32x16_bf16 v[16:31], v[128:131], v[196:199], v[16:31]
	s_add_i32 s4, s76, 1
	s_cmp_lg_u32 s76, 2
	s_cselect_b32 s76, s4, 0
	s_add_i32 s4, s74, 1
	s_cmp_lg_u32 s74, 2
	s_cselect_b32 s74, s4, 0
	s_add_u32 s22, s22, 0x20000
	v_mfma_f32_32x32x16_bf16 v[16:31], v[136:139], v[200:203], v[16:31]
	s_addc_u32 s23, s23, 0
	s_add_i32 s86, s86, 1
	s_cmp_eq_u32 s22, 0x800000
	s_waitcnt lgkmcnt(0)
	v_mfma_f32_32x32x16_bf16 v[16:31], v[132:135], v[204:207], v[16:31]
	v_mfma_f32_32x32x16_bf16 v[16:31], v[140:143], v[232:235], v[16:31]
	s_cbranch_scc1 .LBB0_521
	v_mov_b32_e32 v232, v144
	s_cmp_eq_u32 s22, 0x7e0000
	s_mov_b64 s[4:5], -1
	s_cbranch_scc1 .LBB0_510

.LBB0_910:
	v_cndmask_b32_e64 v231, v234, v231, s[4:5]
	v_mul_f32_e32 v192, 0xbe0293ee, v231
	v_fmamk_f32 v144, v144, 0x3e0293ee, v192
	v_fmamk_f32 v145, v145, 0x3e0293ee, v192
	v_fmamk_f32 v146, v146, 0x3e0293ee, v192
	v_fmamk_f32 v147, v147, 0x3e0293ee, v192
	v_fmamk_f32 v148, v148, 0x3e0293ee, v192
	v_fmamk_f32 v149, v149, 0x3e0293ee, v192
	v_fmamk_f32 v150, v150, 0x3e0293ee, v192
	v_fmamk_f32 v151, v151, 0x3e0293ee, v192
	v_fmamk_f32 v152, v152, 0x3e0293ee, v192
	v_fmamk_f32 v153, v153, 0x3e0293ee, v192
	v_fmamk_f32 v154, v154, 0x3e0293ee, v192
	v_fmamk_f32 v155, v155, 0x3e0293ee, v192
	v_fmamk_f32 v156, v156, 0x3e0293ee, v192
	v_fmamk_f32 v157, v157, 0x3e0293ee, v192
	v_fmamk_f32 v158, v158, 0x3e0293ee, v192
	v_fmamk_f32 v159, v159, 0x3e0293ee, v192
	v_fmamk_f32 v128, v128, 0x3e0293ee, v192
	v_fmamk_f32 v129, v129, 0x3e0293ee, v192
	v_fmamk_f32 v130, v130, 0x3e0293ee, v192
	v_fmamk_f32 v131, v131, 0x3e0293ee, v192
	v_fmamk_f32 v132, v132, 0x3e0293ee, v192
	v_fmamk_f32 v133, v133, 0x3e0293ee, v192
	v_fmamk_f32 v134, v134, 0x3e0293ee, v192
	v_fmamk_f32 v135, v135, 0x3e0293ee, v192
	v_fmamk_f32 v136, v136, 0x3e0293ee, v192
	v_fmamk_f32 v137, v137, 0x3e0293ee, v192
	v_fmamk_f32 v138, v138, 0x3e0293ee, v192
	v_fmamk_f32 v139, v139, 0x3e0293ee, v192
	v_fmamk_f32 v140, v140, 0x3e0293ee, v192
	v_fmamk_f32 v141, v141, 0x3e0293ee, v192
	v_fmamk_f32 v142, v142, 0x3e0293ee, v192
	v_fmac_f32_e32 v192, 0x3e0293ee, v143
	v_exp_f32_e32 v143, v144
	v_exp_f32_e32 v145, v145
	v_exp_f32_e32 v146, v146
	v_exp_f32_e32 v147, v147
	v_exp_f32_e32 v148, v148
	v_exp_f32_e32 v193, v128
	v_exp_f32_e32 v149, v149
	v_add_f32_e32 v128, v145, v143
	v_exp_f32_e32 v150, v150
	v_add_f32_e32 v128, v146, v128
	v_exp_f32_e32 v151, v151
	v_add_f32_e32 v128, v147, v128
	v_exp_f32_e32 v152, v152
	v_add_f32_e32 v128, v148, v128
	v_exp_f32_e32 v153, v153
	v_add_f32_e32 v128, v149, v128
	v_exp_f32_e32 v154, v154
	v_add_f32_e32 v128, v150, v128
	v_exp_f32_e32 v155, v155
	v_add_f32_e32 v128, v151, v128
	v_exp_f32_e32 v156, v156
	v_add_f32_e32 v128, v152, v128
	v_exp_f32_e32 v157, v157
	v_add_f32_e32 v128, v153, v128
	v_exp_f32_e32 v158, v158
	v_add_f32_e32 v128, v154, v128
	v_exp_f32_e32 v159, v159
	v_add_f32_e32 v128, v155, v128
	v_add_f32_e32 v128, v156, v128
	v_exp_f32_e32 v194, v129
	v_add_f32_e32 v128, v157, v128
	v_exp_f32_e32 v195, v130
	v_add_f32_e32 v128, v158, v128
	v_exp_f32_e32 v196, v131
	v_add_f32_e32 v128, v159, v128
	v_exp_f32_e32 v197, v132
	v_add_f32_e32 v128, v193, v128
	v_exp_f32_e32 v198, v133
	v_add_f32_e32 v128, v194, v128
	v_exp_f32_e32 v199, v134
	v_add_f32_e32 v128, v195, v128
	v_exp_f32_e32 v135, v135
	v_add_f32_e32 v128, v196, v128
	v_exp_f32_e32 v200, v136
	v_add_f32_e32 v128, v197, v128
	v_exp_f32_e32 v201, v137
	v_add_f32_e32 v128, v198, v128
	v_exp_f32_e32 v202, v138
	v_add_f32_e32 v128, v199, v128
	v_exp_f32_e32 v203, v139
	v_add_f32_e32 v128, v135, v128
	v_exp_f32_e32 v204, v140
	v_add_f32_e32 v128, v200, v128
	v_exp_f32_e32 v205, v141
	v_add_f32_e32 v128, v201, v128
	v_exp_f32_e32 v206, v142
	v_add_f32_e32 v128, v202, v128
	v_exp_f32_e32 v192, v192
	v_add_f32_e32 v128, v203, v128
	v_add_f32_e32 v128, v204, v128
	v_add_f32_e32 v128, v205, v128
	v_add_f32_e32 v128, v206, v128
	v_add_f32_e32 v128, v192, v128
	v_mov_b32_e32 v129, v128
	s_nop 1
	v_permlane32_swap_b32_e32 v128, v129
	v_add_f32_e32 v144, v128, v129
	v_fmac_f32_e32 v144, v232, v233
	v_cvt_pk_bf16_f32 v128, v143, v145
	v_cvt_pk_bf16_f32 v129, v146, v147
	v_cvt_pk_bf16_f32 v130, v148, v149
	v_cvt_pk_bf16_f32 v131, v150, v151
	v_cvt_pk_bf16_f32 v136, v152, v153
	v_cvt_pk_bf16_f32 v137, v154, v155
	v_cvt_pk_bf16_f32 v138, v156, v157
	v_cvt_pk_bf16_f32 v139, v158, v159
	v_cvt_pk_bf16_f32 v132, v193, v194
	v_cvt_pk_bf16_f32 v133, v195, v196
	v_cvt_pk_bf16_f32 v134, v197, v198
	v_cvt_pk_bf16_f32 v135, v199, v135
	v_cvt_pk_bf16_f32 v140, v200, v201
	v_cvt_pk_bf16_f32 v141, v202, v203
	v_cvt_pk_bf16_f32 v142, v204, v205
	v_cvt_pk_bf16_f32 v143, v206, v192
	v_lshl_add_u32 v145, s80, 15, v230
	ds_read_b64_tr_b16 v[146:147], v145 offset:0
	ds_read_b64_tr_b16 v[148:149], v145 offset:4096
	ds_read_b64_tr_b16 v[150:151], v145 offset:8192
	ds_read_b64_tr_b16 v[152:153], v145 offset:12288
	ds_read_b64_tr_b16 v[154:155], v145 offset:16384
	ds_read_b64_tr_b16 v[156:157], v145 offset:20480
	ds_read_b64_tr_b16 v[192:193], v145 offset:24576
	ds_read_b64_tr_b16 v[194:195], v145 offset:28672
	ds_read_b64_tr_b16 v[196:197], v145 offset:512
	ds_read_b64_tr_b16 v[198:199], v145 offset:4608
	ds_read_b64_tr_b16 v[200:201], v145 offset:8704
	ds_read_b64_tr_b16 v[202:203], v145 offset:12800
	ds_read_b64_tr_b16 v[204:205], v145 offset:16896
	ds_read_b64_tr_b16 v[206:207], v145 offset:20992
	s_waitcnt lgkmcnt(10)
	s_nop 0
	v_mfma_f32_32x32x16_bf16 v[0:15], v[128:131], v[146:149], v[0:15]
	v_mfma_f32_32x32x16_bf16 v[0:15], v[136:139], v[150:153], v[0:15]
	ds_read_b64_tr_b16 v[232:233], v145 offset:25088
	ds_read_b64_tr_b16 v[234:235], v145 offset:29184
	ds_read_b64_tr_b16 v[146:147], v145 offset:1024
	ds_read_b64_tr_b16 v[148:149], v145 offset:5120
	s_waitcnt lgkmcnt(10)
	v_mfma_f32_32x32x16_bf16 v[0:15], v[132:135], v[154:157], v[0:15]
	v_mfma_f32_32x32x16_bf16 v[0:15], v[140:143], v[192:195], v[0:15]
	ds_read_b64_tr_b16 v[150:151], v145 offset:9216
	ds_read_b64_tr_b16 v[152:153], v145 offset:13312
	ds_read_b64_tr_b16 v[154:155], v145 offset:17408
	ds_read_b64_tr_b16 v[156:157], v145 offset:21504
	s_waitcnt lgkmcnt(10)
	v_mfma_f32_32x32x16_bf16 v[112:127], v[128:131], v[196:199], v[112:127]
	v_mfma_f32_32x32x16_bf16 v[112:127], v[136:139], v[200:203], v[112:127]
	ds_read_b64_tr_b16 v[192:193], v145 offset:25600
	ds_read_b64_tr_b16 v[194:195], v145 offset:29696
	ds_read_b64_tr_b16 v[196:197], v145 offset:1536
	ds_read_b64_tr_b16 v[198:199], v145 offset:5632
	s_waitcnt lgkmcnt(10)
	v_mfma_f32_32x32x16_bf16 v[112:127], v[132:135], v[204:207], v[112:127]
	v_mfma_f32_32x32x16_bf16 v[112:127], v[140:143], v[232:235], v[112:127]
	ds_read_b64_tr_b16 v[200:201], v145 offset:9728
	ds_read_b64_tr_b16 v[202:203], v145 offset:13824
	ds_read_b64_tr_b16 v[204:205], v145 offset:17920
	ds_read_b64_tr_b16 v[206:207], v145 offset:22016
	s_waitcnt lgkmcnt(10)
	v_mfma_f32_32x32x16_bf16 v[96:111], v[128:131], v[146:149], v[96:111]
	v_mfma_f32_32x32x16_bf16 v[96:111], v[136:139], v[150:153], v[96:111]
	ds_read_b64_tr_b16 v[232:233], v145 offset:26112
	ds_read_b64_tr_b16 v[234:235], v145 offset:30208
	ds_read_b64_tr_b16 v[146:147], v145 offset:2048
	ds_read_b64_tr_b16 v[148:149], v145 offset:6144
	s_waitcnt lgkmcnt(10)
	v_mfma_f32_32x32x16_bf16 v[96:111], v[132:135], v[154:157], v[96:111]
	v_mfma_f32_32x32x16_bf16 v[96:111], v[140:143], v[192:195], v[96:111]
	ds_read_b64_tr_b16 v[150:151], v145 offset:10240
	ds_read_b64_tr_b16 v[152:153], v145 offset:14336
	ds_read_b64_tr_b16 v[154:155], v145 offset:18432
	ds_read_b64_tr_b16 v[156:157], v145 offset:22528
	s_waitcnt lgkmcnt(10)
	v_mfma_f32_32x32x16_bf16 v[80:95], v[128:131], v[196:199], v[80:95]
	v_mfma_f32_32x32x16_bf16 v[80:95], v[136:139], v[200:203], v[80:95]
	ds_read_b64_tr_b16 v[192:193], v145 offset:26624
	ds_read_b64_tr_b16 v[194:195], v145 offset:30720
	ds_read_b64_tr_b16 v[196:197], v145 offset:2560
	ds_read_b64_tr_b16 v[198:199], v145 offset:6656
	s_waitcnt lgkmcnt(10)
	v_mfma_f32_32x32x16_bf16 v[80:95], v[132:135], v[204:207], v[80:95]
	v_mfma_f32_32x32x16_bf16 v[80:95], v[140:143], v[232:235], v[80:95]
	ds_read_b64_tr_b16 v[200:201], v145 offset:10752
	ds_read_b64_tr_b16 v[202:203], v145 offset:14848
	ds_read_b64_tr_b16 v[204:205], v145 offset:18944
	ds_read_b64_tr_b16 v[206:207], v145 offset:23040
	s_waitcnt lgkmcnt(10)
	v_mfma_f32_32x32x16_bf16 v[64:79], v[128:131], v[146:149], v[64:79]
	v_mfma_f32_32x32x16_bf16 v[64:79], v[136:139], v[150:153], v[64:79]
	ds_read_b64_tr_b16 v[232:233], v145 offset:27136
	ds_read_b64_tr_b16 v[234:235], v145 offset:31232
	ds_read_b64_tr_b16 v[146:147], v145 offset:3072
	ds_read_b64_tr_b16 v[148:149], v145 offset:7168
	s_waitcnt lgkmcnt(10)
	v_mfma_f32_32x32x16_bf16 v[64:79], v[132:135], v[154:157], v[64:79]
	v_mfma_f32_32x32x16_bf16 v[64:79], v[140:143], v[192:195], v[64:79]
	ds_read_b64_tr_b16 v[150:151], v145 offset:11264
	ds_read_b64_tr_b16 v[152:153], v145 offset:15360
	ds_read_b64_tr_b16 v[154:155], v145 offset:19456
	ds_read_b64_tr_b16 v[156:157], v145 offset:23552
	s_waitcnt lgkmcnt(10)
	v_mfma_f32_32x32x16_bf16 v[48:63], v[128:131], v[196:199], v[48:63]
	v_mfma_f32_32x32x16_bf16 v[48:63], v[136:139], v[200:203], v[48:63]
	ds_read_b64_tr_b16 v[192:193], v145 offset:27648
	ds_read_b64_tr_b16 v[194:195], v145 offset:31744
	ds_read_b64_tr_b16 v[196:197], v145 offset:3584
	ds_read_b64_tr_b16 v[198:199], v145 offset:7680
	s_waitcnt lgkmcnt(10)
	v_mfma_f32_32x32x16_bf16 v[48:63], v[132:135], v[204:207], v[48:63]
	v_mfma_f32_32x32x16_bf16 v[48:63], v[140:143], v[232:235], v[48:63]
	ds_read_b64_tr_b16 v[200:201], v145 offset:11776
	ds_read_b64_tr_b16 v[202:203], v145 offset:15872
	ds_read_b64_tr_b16 v[204:205], v145 offset:19968
	ds_read_b64_tr_b16 v[206:207], v145 offset:24064
	s_waitcnt lgkmcnt(10)
	v_mfma_f32_32x32x16_bf16 v[32:47], v[128:131], v[146:149], v[32:47]
	v_mfma_f32_32x32x16_bf16 v[32:47], v[136:139], v[150:153], v[32:47]
	ds_read_b64_tr_b16 v[232:233], v145 offset:28160
	ds_read_b64_tr_b16 v[234:235], v145 offset:32256
	s_waitcnt lgkmcnt(8)
	v_mfma_f32_32x32x16_bf16 v[32:47], v[132:135], v[154:157], v[32:47]
	v_mfma_f32_32x32x16_bf16 v[32:47], v[140:143], v[192:195], v[32:47]
	s_waitcnt lgkmcnt(4)
	v_mfma_f32_32x32x16_bf16 v[16:31], v[128:131], v[196:199], v[16:31]
	s_add_i32 s4, s80, 1
	s_cmp_lg_u32 s80, 2
	s_cselect_b32 s80, s4, 0
	s_add_i32 s4, s78, 1
	s_cmp_lg_u32 s78, 2
	s_cselect_b32 s78, s4, 0
	s_add_u32 s22, s22, 0x20000
	v_mfma_f32_32x32x16_bf16 v[16:31], v[136:139], v[200:203], v[16:31]
	s_addc_u32 s23, s23, 0
	s_add_i32 s86, s86, 1
	s_cmp_eq_u32 s22, 0x800000
	s_waitcnt lgkmcnt(0)
	v_mfma_f32_32x32x16_bf16 v[16:31], v[132:135], v[204:207], v[16:31]
	v_mfma_f32_32x32x16_bf16 v[16:31], v[140:143], v[232:235], v[16:31]
	s_cbranch_scc1 .LBB0_914
	v_mov_b32_e32 v232, v144
	s_cmp_eq_u32 s22, 0x7e0000
	s_mov_b64 s[4:5], -1
	s_cbranch_scc1 .LBB0_903
